# conversion items: the four p loads of a thread issued together (cvt_pk RNE) on top of the pooling fast path
# baseline (speedup 1.0000x reference)
; __device__ __forceinline__ unsigned pk2(float lo, float hi) { return f2bf(lo) | (f2bf(hi) << 16); }
; #define INP(i) ((const float*)ldp(ptab, (i)))
; __global__ void __launch_bounds__(NWAVES * 64, 2) fwd_megakernel(Args args) {
;     ...
;                 { const f32x4* p4 = (const f32x4*)INP(1); uint2* pb = (uint2*)WSP(bfu, WS_PB);
; #pragma unroll
;                   for (int k2 = 0; k2 < 4; ++k2) { const int i = ci * 2048 + k2 * 512 + (int)threadIdx.x; const f32x4 v = __builtin_nontemporal_load(p4 + i); pb[i] = make_uint2(pk2(v[0], v[1]), pk2(v[2], v[3])); } }
;                 __syncthreads(); continue; }
.LBB0_262:
	v_mov_b32_e32 v0, s84
	ds_read_b64 v[0:1], v0
	v_lshl_or_b32 v220, s4, 11, v227
	v_lshlrev_b32_e32 v4, 4, v220
	v_lshlrev_b32_e32 v5, 3, v220
	s_waitcnt lgkmcnt(0)
	v_readfirstlane_b32 s1, v1
	v_readfirstlane_b32 s0, v0
	v_add_u32_e32 v25, 0x2000, v4
	v_add_u32_e32 v29, 0x1000, v5
	v_add_u32_e32 v26, 0x4000, v4
	v_add_u32_e32 v30, 0x2000, v5
	v_add_u32_e32 v27, 0x6000, v4
	v_add_u32_e32 v31, 0x3000, v5
	s_nop 1
	global_load_dwordx4 v[8:11], v4, s[0:1] nt
	global_load_dwordx4 v[12:15], v25, s[0:1] nt
	global_load_dwordx4 v[16:19], v26, s[0:1] nt
	global_load_dwordx4 v[20:23], v27, s[0:1] nt
	s_waitcnt vmcnt(3)
	v_cvt_pk_bf16_f32 v32, v8, v9
	v_cvt_pk_bf16_f32 v33, v10, v11
	global_store_dwordx2 v5, v[32:33], s[30:31]
	s_waitcnt vmcnt(3)
	v_cvt_pk_bf16_f32 v34, v12, v13
	v_cvt_pk_bf16_f32 v35, v14, v15
	global_store_dwordx2 v29, v[34:35], s[30:31]
	s_waitcnt vmcnt(3)
	v_cvt_pk_bf16_f32 v36, v16, v17
	v_cvt_pk_bf16_f32 v37, v18, v19
	global_store_dwordx2 v30, v[36:37], s[30:31]
	s_waitcnt vmcnt(3)
	v_cvt_pk_bf16_f32 v38, v20, v21
	v_cvt_pk_bf16_f32 v39, v22, v23
	global_store_dwordx2 v31, v[38:39], s[30:31]
	s_waitcnt lgkmcnt(0)
	s_barrier
